# hand-written MLA in-proj epilogue for ckv/cq/kpe tiles: row sums of squares batched (one swizzle wait), saddr stores, kpe rope tables double-buffered
# speedup vs baseline: 1.0213x; 1.0003x over previous
.LBB0_687:
	s_andn2_b64 vcc, exec, s[4:5]
	s_cbranch_vccnz .LBB0_971
	s_cmp_eq_u32 s39, 1
	s_mov_b64 s[4:5], -1
	s_cbranch_scc1 .LBB0_873
	s_load_dwordx2 s[4:5], s[0:1], 0xd0
	v_readlane_b32 s48, v254, 36
	v_readlane_b32 s49, v254, 45
	v_readlane_b32 s50, v255, 29
	v_readlane_b32 s51, v255, 25
	v_readlane_b32 s58, v255, 22
	s_lshl_b32 s59, s48, 8
	s_add_u32 s59, s59, s49
	s_sub_u32 s96, s48, 32
	s_and_b32 s97, s96, 3
	s_lshl_b32 s97, s97, 8
	s_add_u32 s97, s97, s49
	s_mov_b32 s33, s59
	s_cmp_lt_u32 s48, 32
	s_cbranch_scc1 .Lm0_ctx
	s_lshr_b32 s33, s96, 2
	s_mul_i32 s33, s33, 0x600
	s_add_u32 s33, s33, 0x2200
	s_add_u32 s33, s33, s97
.Lm0_ctx:
	v_lshl_add_u32 v134, v191, 4, v189
	s_lshl_b32 s24, s50, 1
	s_cmp_eq_u32 s74, 0
	s_cbranch_scc1 .Lm0_setup0
	v_lshlrev_b32_e32 v134, 5, v134
	s_lshl_b32 s25, s59, 5
	s_lshl_b32 s35, s51, 2
	s_add_u32 s25, s25, s35
	s_add_u32 s25, s25, 0x280000
	s_mul_i32 s35, s59, 0x300
	s_add_u32 s35, s35, s24
	s_add_u32 s35, s35, 0xb000000
	s_mov_b32 s33, 0x3000
	s_mov_b32 s34, 0xf000
	v_mul_u32_u24_e32 v130, 0x300, v189
	v_lshl_add_u32 v130, v191, 4, v130
	s_cmp_eq_u32 s74, 2
	s_cbranch_scc0 .Lm0_common
	s_add_u32 s35, s35, 0x200
	s_add_u32 s25, s25, 16
	s_branch .Lm0_common
.Lm0_setup0:
	v_lshlrev_b32_e32 v134, 4, v134
	s_lshl_b32 s25, s59, 4
	s_lshl_b32 s35, s51, 2
	s_add_u32 s25, s25, s35
	s_add_u32 s25, s25, 0x200000
	s_lshl_b32 s35, s33, 9
	s_add_u32 s35, s35, s24
	s_mul_i32 s36, s58, 0x700000
	s_add_u32 s35, s35, s36
	s_add_u32 s35, s35, 0xb900000
	v_lshlrev_b32_e32 v130, 9, v189
	v_lshl_add_u32 v130, v191, 4, v130
	s_mov_b32 s36, s33
	s_mov_b32 s33, 0x2000
	s_mov_b32 s34, 0xa000
.Lm0_common:
	s_waitcnt lgkmcnt(0)
	s_add_u32 s6, s4, s35
	s_addc_u32 s7, s5, 0
	s_mov_b32 s35, 0x800
	s_cmp_eq_u32 s74, 0
	s_cselect_b32 s35, s35, 0x1000
	s_add_u32 s24, s4, s25
	s_addc_u32 s25, s5, 0
	s_cmp_lt_u32 s74, 2
	s_cbranch_scc1 .Lm0_P01
	s_cmp_lg_u32 s51, 0
	s_cbranch_scc1 .Lm0_P2a
	s_mov_b32 s36, s59
	s_cmp_lt_u32 s48, 32
	s_cbranch_scc1 .Lm0_kctx
	s_lshr_b32 s36, s96, 2
	s_mul_i32 s36, s36, 0x600
	s_add_u32 s36, s36, 0x2200
	s_add_u32 s36, s36, s97
.Lm0_kctx:
	s_lshl_b32 s36, s36, 6
	s_mul_i32 s37, s58, 0xe0000
	s_add_u32 s36, s36, s37
	s_add_u32 s36, s36, 0xc700000
	s_add_u32 s48, s4, s36
	s_addc_u32 s49, s5, 0
	v_lshlrev_b32_e32 v131, 6, v189
	v_lshl_add_u32 v131, v191, 4, v131
	s_sub_u32 s36, s96, 0
	s_cmp_gt_i32 s96, -1
	s_cbranch_scc0 .Lm0_P2b
	s_lshl_b32 s36, s97, 6
	s_add_u32 s8, s4, s36
	s_addc_u32 s9, s5, 0
	s_add_u32 s8, s8, 0x1c0000
	s_addc_u32 s9, s9, 0
	v_mov_b32_e32 v132, v131
	v_add_u32_e32 v133, 0x10000, v131
	s_branch .Lm0_P2c
.Lm0_P01:
	v_cmp_eq_u32_e64 s[50:51], 1, v191
	v_cmp_eq_u32_e64 s[58:59], 2, v191
	v_cmp_eq_u32_e64 s[96:97], 3, v191
	v_mul_f32_e32 v136, v127, v127
	v_fmac_f32_e32 v136, v126, v126
	v_fmac_f32_e32 v136, v128, v128
	v_mul_f32_e32 v160, v129, v129
	v_mul_f32_e32 v161, v123, v123
	v_add_f32_e32 v136, v160, v136
	v_fmac_f32_e32 v136, v122, v122
	v_mul_f32_e32 v160, v125, v125
	v_add_f32_e32 v136, v161, v136
	v_fmac_f32_e32 v136, v124, v124
	v_add_f32_e32 v136, v160, v136
	v_mul_f32_e32 v160, v118, v118
	v_mul_f32_e32 v161, v119, v119
	v_add_f32_e32 v136, v160, v136
	v_add_f32_e32 v136, v161, v136
	v_mul_f32_e32 v160, v120, v120
	v_mul_f32_e32 v161, v121, v121
	v_add_f32_e32 v136, v160, v136
	v_add_f32_e32 v136, v161, v136
	v_mul_f32_e32 v160, v114, v114
	v_mul_f32_e32 v161, v115, v115
	v_add_f32_e32 v136, v160, v136
	v_add_f32_e32 v136, v161, v136
	v_mul_f32_e32 v160, v116, v116
	v_mul_f32_e32 v161, v117, v117
	v_add_f32_e32 v136, v160, v136
	v_add_f32_e32 v136, v161, v136
	v_mul_f32_e32 v137, v109, v109
	v_fmac_f32_e32 v137, v108, v108
	v_fmac_f32_e32 v137, v110, v110
	v_mul_f32_e32 v160, v111, v111
	v_mul_f32_e32 v161, v105, v105
	v_add_f32_e32 v137, v160, v137
	v_fmac_f32_e32 v137, v104, v104
	v_mul_f32_e32 v160, v107, v107
	v_add_f32_e32 v137, v161, v137
	v_fmac_f32_e32 v137, v106, v106
	v_add_f32_e32 v137, v160, v137
	v_mul_f32_e32 v160, v100, v100
	v_mul_f32_e32 v161, v101, v101
	v_add_f32_e32 v137, v160, v137
	v_add_f32_e32 v137, v161, v137
	v_mul_f32_e32 v160, v102, v102
	v_mul_f32_e32 v161, v103, v103
	v_add_f32_e32 v137, v160, v137
	v_add_f32_e32 v137, v161, v137
	v_mul_f32_e32 v160, v96, v96
	v_mul_f32_e32 v161, v97, v97
	v_add_f32_e32 v137, v160, v137
	v_add_f32_e32 v137, v161, v137
	v_mul_f32_e32 v160, v98, v98
	v_mul_f32_e32 v161, v99, v99
	v_add_f32_e32 v137, v160, v137
	v_add_f32_e32 v137, v161, v137
	v_mul_f32_e32 v138, v93, v93
	v_fmac_f32_e32 v138, v92, v92
	v_fmac_f32_e32 v138, v94, v94
	v_mul_f32_e32 v160, v95, v95
	v_mul_f32_e32 v161, v89, v89
	v_add_f32_e32 v138, v160, v138
	v_fmac_f32_e32 v138, v88, v88
	v_mul_f32_e32 v160, v91, v91
	v_add_f32_e32 v138, v161, v138
	v_fmac_f32_e32 v138, v90, v90
	v_add_f32_e32 v138, v160, v138
	v_mul_f32_e32 v160, v84, v84
	v_mul_f32_e32 v161, v85, v85
	v_add_f32_e32 v138, v160, v138
	v_add_f32_e32 v138, v161, v138
	v_mul_f32_e32 v160, v86, v86
	v_mul_f32_e32 v161, v87, v87
	v_add_f32_e32 v138, v160, v138
	v_add_f32_e32 v138, v161, v138
	v_mul_f32_e32 v160, v80, v80
	v_mul_f32_e32 v161, v81, v81
	v_add_f32_e32 v138, v160, v138
	v_add_f32_e32 v138, v161, v138
	v_mul_f32_e32 v160, v82, v82
	v_mul_f32_e32 v161, v83, v83
	v_add_f32_e32 v138, v160, v138
	v_add_f32_e32 v138, v161, v138
	v_mul_f32_e32 v139, v77, v77
	v_fmac_f32_e32 v139, v76, v76
	v_fmac_f32_e32 v139, v78, v78
	v_mul_f32_e32 v160, v79, v79
	v_mul_f32_e32 v161, v73, v73
	v_add_f32_e32 v139, v160, v139
	v_fmac_f32_e32 v139, v72, v72
	v_mul_f32_e32 v160, v75, v75
	v_add_f32_e32 v139, v161, v139
	v_fmac_f32_e32 v139, v74, v74
	v_add_f32_e32 v139, v160, v139
	v_mul_f32_e32 v160, v68, v68
	v_mul_f32_e32 v161, v69, v69
	v_add_f32_e32 v139, v160, v139
	v_add_f32_e32 v139, v161, v139
	v_mul_f32_e32 v160, v70, v70
	v_mul_f32_e32 v161, v71, v71
	v_add_f32_e32 v139, v160, v139
	v_add_f32_e32 v139, v161, v139
	v_mul_f32_e32 v160, v64, v64
	v_mul_f32_e32 v161, v65, v65
	v_add_f32_e32 v139, v160, v139
	v_add_f32_e32 v139, v161, v139
	v_mul_f32_e32 v160, v66, v66
	v_mul_f32_e32 v161, v67, v67
	v_add_f32_e32 v139, v160, v139
	v_add_f32_e32 v139, v161, v139
	v_mul_f32_e32 v140, v61, v61
	v_fmac_f32_e32 v140, v60, v60
	v_fmac_f32_e32 v140, v62, v62
	v_mul_f32_e32 v160, v63, v63
	v_mul_f32_e32 v161, v57, v57
	v_add_f32_e32 v140, v160, v140
	v_fmac_f32_e32 v140, v56, v56
	v_mul_f32_e32 v160, v59, v59
	v_add_f32_e32 v140, v161, v140
	v_fmac_f32_e32 v140, v58, v58
	v_add_f32_e32 v140, v160, v140
	v_mul_f32_e32 v160, v52, v52
	v_mul_f32_e32 v161, v53, v53
	v_add_f32_e32 v140, v160, v140
	v_add_f32_e32 v140, v161, v140
	v_mul_f32_e32 v160, v54, v54
	v_mul_f32_e32 v161, v55, v55
	v_add_f32_e32 v140, v160, v140
	v_add_f32_e32 v140, v161, v140
	v_mul_f32_e32 v160, v48, v48
	v_mul_f32_e32 v161, v49, v49
	v_add_f32_e32 v140, v160, v140
	v_add_f32_e32 v140, v161, v140
	v_mul_f32_e32 v160, v50, v50
	v_mul_f32_e32 v161, v51, v51
	v_add_f32_e32 v140, v160, v140
	v_add_f32_e32 v140, v161, v140
	v_mul_f32_e32 v141, v45, v45
	v_fmac_f32_e32 v141, v44, v44
	v_fmac_f32_e32 v141, v46, v46
	v_mul_f32_e32 v160, v47, v47
	v_mul_f32_e32 v161, v41, v41
	v_add_f32_e32 v141, v160, v141
	v_fmac_f32_e32 v141, v40, v40
	v_mul_f32_e32 v160, v43, v43
	v_add_f32_e32 v141, v161, v141
	v_fmac_f32_e32 v141, v42, v42
	v_add_f32_e32 v141, v160, v141
	v_mul_f32_e32 v160, v36, v36
	v_mul_f32_e32 v161, v37, v37
	v_add_f32_e32 v141, v160, v141
	v_add_f32_e32 v141, v161, v141
	v_mul_f32_e32 v160, v38, v38
	v_mul_f32_e32 v161, v39, v39
	v_add_f32_e32 v141, v160, v141
	v_add_f32_e32 v141, v161, v141
	v_mul_f32_e32 v160, v32, v32
	v_mul_f32_e32 v161, v33, v33
	v_add_f32_e32 v141, v160, v141
	v_add_f32_e32 v141, v161, v141
	v_mul_f32_e32 v160, v34, v34
	v_mul_f32_e32 v161, v35, v35
	v_add_f32_e32 v141, v160, v141
	v_add_f32_e32 v141, v161, v141
	v_mul_f32_e32 v142, v29, v29
	v_fmac_f32_e32 v142, v28, v28
	v_fmac_f32_e32 v142, v30, v30
	v_mul_f32_e32 v160, v31, v31
	v_mul_f32_e32 v161, v25, v25
	v_add_f32_e32 v142, v160, v142
	v_fmac_f32_e32 v142, v24, v24
	v_mul_f32_e32 v160, v27, v27
	v_add_f32_e32 v142, v161, v142
	v_fmac_f32_e32 v142, v26, v26
	v_add_f32_e32 v142, v160, v142
	v_mul_f32_e32 v160, v20, v20
	v_mul_f32_e32 v161, v21, v21
	v_add_f32_e32 v142, v160, v142
	v_add_f32_e32 v142, v161, v142
	v_mul_f32_e32 v160, v22, v22
	v_mul_f32_e32 v161, v23, v23
	v_add_f32_e32 v142, v160, v142
	v_add_f32_e32 v142, v161, v142
	v_mul_f32_e32 v160, v16, v16
	v_mul_f32_e32 v161, v17, v17
	v_add_f32_e32 v142, v160, v142
	v_add_f32_e32 v142, v161, v142
	v_mul_f32_e32 v160, v18, v18
	v_mul_f32_e32 v161, v19, v19
	v_add_f32_e32 v142, v160, v142
	v_add_f32_e32 v142, v161, v142
	v_mul_f32_e32 v143, v13, v13
	v_fmac_f32_e32 v143, v12, v12
	v_fmac_f32_e32 v143, v14, v14
	v_mul_f32_e32 v160, v15, v15
	v_mul_f32_e32 v161, v5, v5
	v_add_f32_e32 v143, v160, v143
	v_fmac_f32_e32 v143, v4, v4
	v_mul_f32_e32 v160, v7, v7
	v_add_f32_e32 v143, v161, v143
	v_fmac_f32_e32 v143, v6, v6
	v_add_f32_e32 v143, v160, v143
	v_mul_f32_e32 v160, v8, v8
	v_mul_f32_e32 v161, v9, v9
	v_add_f32_e32 v143, v160, v143
	v_add_f32_e32 v143, v161, v143
	v_mul_f32_e32 v160, v10, v10
	v_mul_f32_e32 v161, v11, v11
	v_add_f32_e32 v143, v160, v143
	v_add_f32_e32 v143, v161, v143
	v_mul_f32_e32 v160, v0, v0
	v_mul_f32_e32 v161, v1, v1
	v_add_f32_e32 v143, v160, v143
	v_add_f32_e32 v143, v161, v143
	v_mul_f32_e32 v160, v2, v2
	v_mul_f32_e32 v161, v3, v3
	v_add_f32_e32 v143, v160, v143
	v_add_f32_e32 v143, v161, v143
	ds_swizzle_b32 v144, v136 offset:swizzle(SWAP,16)
	ds_swizzle_b32 v145, v137 offset:swizzle(SWAP,16)
	ds_swizzle_b32 v146, v138 offset:swizzle(SWAP,16)
	ds_swizzle_b32 v147, v139 offset:swizzle(SWAP,16)
	ds_swizzle_b32 v148, v140 offset:swizzle(SWAP,16)
	ds_swizzle_b32 v149, v141 offset:swizzle(SWAP,16)
	ds_swizzle_b32 v150, v142 offset:swizzle(SWAP,16)
	ds_swizzle_b32 v151, v143 offset:swizzle(SWAP,16)
	s_waitcnt lgkmcnt(0)
	v_add_f32_e32 v136, v136, v144
	v_add_f32_e32 v137, v137, v145
	v_add_f32_e32 v138, v138, v146
	v_add_f32_e32 v139, v139, v147
	v_add_f32_e32 v140, v140, v148
	v_add_f32_e32 v141, v141, v149
	v_add_f32_e32 v142, v142, v150
	v_add_f32_e32 v143, v143, v151
	v_mov_b32_e32 v144, v136
	v_mov_b32_e32 v145, v137
	v_mov_b32_e32 v146, v138
	v_mov_b32_e32 v147, v139
	v_mov_b32_e32 v148, v140
	v_mov_b32_e32 v149, v141
	v_mov_b32_e32 v150, v142
	v_mov_b32_e32 v151, v143
	s_nop 1
	v_permlane32_swap_b32 v136, v144
	v_permlane32_swap_b32 v137, v145
	v_permlane32_swap_b32 v138, v146
	v_permlane32_swap_b32 v139, v147
	v_permlane32_swap_b32 v140, v148
	v_permlane32_swap_b32 v141, v149
	v_permlane32_swap_b32 v142, v150
	v_permlane32_swap_b32 v143, v151
	s_nop 1
	v_add_f32_e32 v136, v136, v144
	v_add_f32_e32 v137, v137, v145
	v_add_f32_e32 v138, v138, v146
	v_add_f32_e32 v139, v139, v147
	v_add_f32_e32 v140, v140, v148
	v_add_f32_e32 v141, v141, v149
	v_add_f32_e32 v142, v142, v150
	v_add_f32_e32 v143, v143, v151
	v_cvt_pk_bf16_f32 v152, v126, v127
	v_cvt_pk_bf16_f32 v153, v128, v129
	v_cvt_pk_bf16_f32 v154, v122, v123
	v_cvt_pk_bf16_f32 v155, v124, v125
	global_store_dwordx4 v130, v[152:155], s[6:7] sc1
	v_cvt_pk_bf16_f32 v156, v118, v119
	v_cvt_pk_bf16_f32 v157, v120, v121
	v_cvt_pk_bf16_f32 v158, v114, v115
	v_cvt_pk_bf16_f32 v159, v116, v117
	global_store_dwordx4 v130, v[156:159], s[6:7] offset:256 sc1
	s_add_u32 s6, s6, s33
	s_addc_u32 s7, s7, 0
	v_cvt_pk_bf16_f32 v152, v108, v109
	v_cvt_pk_bf16_f32 v153, v110, v111
	v_cvt_pk_bf16_f32 v154, v104, v105
	v_cvt_pk_bf16_f32 v155, v106, v107
	global_store_dwordx4 v130, v[152:155], s[6:7] sc1
	v_cvt_pk_bf16_f32 v156, v100, v101
	v_cvt_pk_bf16_f32 v157, v102, v103
	v_cvt_pk_bf16_f32 v158, v96, v97
	v_cvt_pk_bf16_f32 v159, v98, v99
	global_store_dwordx4 v130, v[156:159], s[6:7] offset:256 sc1
	s_add_u32 s6, s6, s33
	s_addc_u32 s7, s7, 0
	v_cvt_pk_bf16_f32 v152, v92, v93
	v_cvt_pk_bf16_f32 v153, v94, v95
	v_cvt_pk_bf16_f32 v154, v88, v89
	v_cvt_pk_bf16_f32 v155, v90, v91
	global_store_dwordx4 v130, v[152:155], s[6:7] sc1
	v_cvt_pk_bf16_f32 v156, v84, v85
	v_cvt_pk_bf16_f32 v157, v86, v87
	v_cvt_pk_bf16_f32 v158, v80, v81
	v_cvt_pk_bf16_f32 v159, v82, v83
	global_store_dwordx4 v130, v[156:159], s[6:7] offset:256 sc1
	s_add_u32 s6, s6, s33
	s_addc_u32 s7, s7, 0
	v_cvt_pk_bf16_f32 v152, v76, v77
	v_cvt_pk_bf16_f32 v153, v78, v79
	v_cvt_pk_bf16_f32 v154, v72, v73
	v_cvt_pk_bf16_f32 v155, v74, v75
	global_store_dwordx4 v130, v[152:155], s[6:7] sc1
	v_cvt_pk_bf16_f32 v156, v68, v69
	v_cvt_pk_bf16_f32 v157, v70, v71
	v_cvt_pk_bf16_f32 v158, v64, v65
	v_cvt_pk_bf16_f32 v159, v66, v67
	global_store_dwordx4 v130, v[156:159], s[6:7] offset:256 sc1
	s_add_u32 s6, s6, s34
	s_addc_u32 s7, s7, 0
	v_cvt_pk_bf16_f32 v152, v60, v61
	v_cvt_pk_bf16_f32 v153, v62, v63
	v_cvt_pk_bf16_f32 v154, v56, v57
	v_cvt_pk_bf16_f32 v155, v58, v59
	global_store_dwordx4 v130, v[152:155], s[6:7] sc1
	v_cvt_pk_bf16_f32 v156, v52, v53
	v_cvt_pk_bf16_f32 v157, v54, v55
	v_cvt_pk_bf16_f32 v158, v48, v49
	v_cvt_pk_bf16_f32 v159, v50, v51
	global_store_dwordx4 v130, v[156:159], s[6:7] offset:256 sc1
	s_add_u32 s6, s6, s33
	s_addc_u32 s7, s7, 0
	v_cvt_pk_bf16_f32 v152, v44, v45
	v_cvt_pk_bf16_f32 v153, v46, v47
	v_cvt_pk_bf16_f32 v154, v40, v41
	v_cvt_pk_bf16_f32 v155, v42, v43
	global_store_dwordx4 v130, v[152:155], s[6:7] sc1
	v_cvt_pk_bf16_f32 v156, v36, v37
	v_cvt_pk_bf16_f32 v157, v38, v39
	v_cvt_pk_bf16_f32 v158, v32, v33
	v_cvt_pk_bf16_f32 v159, v34, v35
	global_store_dwordx4 v130, v[156:159], s[6:7] offset:256 sc1
	s_add_u32 s6, s6, s33
	s_addc_u32 s7, s7, 0
	v_cvt_pk_bf16_f32 v152, v28, v29
	v_cvt_pk_bf16_f32 v153, v30, v31
	v_cvt_pk_bf16_f32 v154, v24, v25
	v_cvt_pk_bf16_f32 v155, v26, v27
	global_store_dwordx4 v130, v[152:155], s[6:7] sc1
	v_cvt_pk_bf16_f32 v156, v20, v21
	v_cvt_pk_bf16_f32 v157, v22, v23
	v_cvt_pk_bf16_f32 v158, v16, v17
	v_cvt_pk_bf16_f32 v159, v18, v19
	global_store_dwordx4 v130, v[156:159], s[6:7] offset:256 sc1
	s_add_u32 s6, s6, s33
	s_addc_u32 s7, s7, 0
	v_cvt_pk_bf16_f32 v152, v12, v13
	v_cvt_pk_bf16_f32 v153, v14, v15
	v_cvt_pk_bf16_f32 v154, v4, v5
	v_cvt_pk_bf16_f32 v155, v6, v7
	global_store_dwordx4 v130, v[152:155], s[6:7] sc1
	v_cvt_pk_bf16_f32 v156, v8, v9
	v_cvt_pk_bf16_f32 v157, v10, v11
	v_cvt_pk_bf16_f32 v158, v0, v1
	v_cvt_pk_bf16_f32 v159, v2, v3
	global_store_dwordx4 v130, v[156:159], s[6:7] offset:256 sc1
	v_cndmask_b32_e64 v160, v136, v137, s[50:51]
	v_cndmask_b32_e64 v160, v160, v138, s[58:59]
	v_cndmask_b32_e64 v160, v160, v139, s[96:97]
	v_cndmask_b32_e64 v161, v140, v141, s[50:51]
	v_cndmask_b32_e64 v161, v161, v142, s[58:59]
	v_cndmask_b32_e64 v161, v161, v143, s[96:97]
	global_store_dword v134, v160, s[24:25] sc1
	s_add_u32 s24, s24, s35
	s_addc_u32 s25, s25, 0
	global_store_dword v134, v161, s[24:25] sc1
	s_branch .LBB0_872
.Lm0_P2a:
	v_cmp_eq_u32_e64 s[50:51], 1, v191
	v_cmp_eq_u32_e64 s[58:59], 2, v191
	v_cmp_eq_u32_e64 s[96:97], 3, v191
	v_mul_f32_e32 v136, v127, v127
	v_fmac_f32_e32 v136, v126, v126
	v_fmac_f32_e32 v136, v128, v128
	v_mul_f32_e32 v160, v129, v129
	v_mul_f32_e32 v161, v123, v123
	v_add_f32_e32 v136, v160, v136
	v_fmac_f32_e32 v136, v122, v122
	v_mul_f32_e32 v160, v125, v125
	v_add_f32_e32 v136, v161, v136
	v_fmac_f32_e32 v136, v124, v124
	v_add_f32_e32 v136, v160, v136
	v_mul_f32_e32 v137, v109, v109
	v_fmac_f32_e32 v137, v108, v108
	v_fmac_f32_e32 v137, v110, v110
	v_mul_f32_e32 v160, v111, v111
	v_mul_f32_e32 v161, v105, v105
	v_add_f32_e32 v137, v160, v137
	v_fmac_f32_e32 v137, v104, v104
	v_mul_f32_e32 v160, v107, v107
	v_add_f32_e32 v137, v161, v137
	v_fmac_f32_e32 v137, v106, v106
	v_add_f32_e32 v137, v160, v137
	v_mul_f32_e32 v138, v93, v93
	v_fmac_f32_e32 v138, v92, v92
	v_fmac_f32_e32 v138, v94, v94
	v_mul_f32_e32 v160, v95, v95
	v_mul_f32_e32 v161, v89, v89
	v_add_f32_e32 v138, v160, v138
	v_fmac_f32_e32 v138, v88, v88
	v_mul_f32_e32 v160, v91, v91
	v_add_f32_e32 v138, v161, v138
	v_fmac_f32_e32 v138, v90, v90
	v_add_f32_e32 v138, v160, v138
	v_mul_f32_e32 v139, v77, v77
	v_fmac_f32_e32 v139, v76, v76
	v_fmac_f32_e32 v139, v78, v78
	v_mul_f32_e32 v160, v79, v79
	v_mul_f32_e32 v161, v73, v73
	v_add_f32_e32 v139, v160, v139
	v_fmac_f32_e32 v139, v72, v72
	v_mul_f32_e32 v160, v75, v75
	v_add_f32_e32 v139, v161, v139
	v_fmac_f32_e32 v139, v74, v74
	v_add_f32_e32 v139, v160, v139
	v_mul_f32_e32 v140, v61, v61
	v_fmac_f32_e32 v140, v60, v60
	v_fmac_f32_e32 v140, v62, v62
	v_mul_f32_e32 v160, v63, v63
	v_mul_f32_e32 v161, v57, v57
	v_add_f32_e32 v140, v160, v140
	v_fmac_f32_e32 v140, v56, v56
	v_mul_f32_e32 v160, v59, v59
	v_add_f32_e32 v140, v161, v140
	v_fmac_f32_e32 v140, v58, v58
	v_add_f32_e32 v140, v160, v140
	v_mul_f32_e32 v141, v45, v45
	v_fmac_f32_e32 v141, v44, v44
	v_fmac_f32_e32 v141, v46, v46
	v_mul_f32_e32 v160, v47, v47
	v_mul_f32_e32 v161, v41, v41
	v_add_f32_e32 v141, v160, v141
	v_fmac_f32_e32 v141, v40, v40
	v_mul_f32_e32 v160, v43, v43
	v_add_f32_e32 v141, v161, v141
	v_fmac_f32_e32 v141, v42, v42
	v_add_f32_e32 v141, v160, v141
	v_mul_f32_e32 v142, v29, v29
	v_fmac_f32_e32 v142, v28, v28
	v_fmac_f32_e32 v142, v30, v30
	v_mul_f32_e32 v160, v31, v31
	v_mul_f32_e32 v161, v25, v25
	v_add_f32_e32 v142, v160, v142
	v_fmac_f32_e32 v142, v24, v24
	v_mul_f32_e32 v160, v27, v27
	v_add_f32_e32 v142, v161, v142
	v_fmac_f32_e32 v142, v26, v26
	v_add_f32_e32 v142, v160, v142
	v_mul_f32_e32 v143, v13, v13
	v_fmac_f32_e32 v143, v12, v12
	v_fmac_f32_e32 v143, v14, v14
	v_mul_f32_e32 v160, v15, v15
	v_mul_f32_e32 v161, v5, v5
	v_add_f32_e32 v143, v160, v143
	v_fmac_f32_e32 v143, v4, v4
	v_mul_f32_e32 v160, v7, v7
	v_add_f32_e32 v143, v161, v143
	v_fmac_f32_e32 v143, v6, v6
	v_add_f32_e32 v143, v160, v143
	ds_swizzle_b32 v144, v136 offset:swizzle(SWAP,16)
	ds_swizzle_b32 v145, v137 offset:swizzle(SWAP,16)
	ds_swizzle_b32 v146, v138 offset:swizzle(SWAP,16)
	ds_swizzle_b32 v147, v139 offset:swizzle(SWAP,16)
	ds_swizzle_b32 v148, v140 offset:swizzle(SWAP,16)
	ds_swizzle_b32 v149, v141 offset:swizzle(SWAP,16)
	ds_swizzle_b32 v150, v142 offset:swizzle(SWAP,16)
	ds_swizzle_b32 v151, v143 offset:swizzle(SWAP,16)
	s_waitcnt lgkmcnt(0)
	v_add_f32_e32 v136, v136, v144
	v_add_f32_e32 v137, v137, v145
	v_add_f32_e32 v138, v138, v146
	v_add_f32_e32 v139, v139, v147
	v_add_f32_e32 v140, v140, v148
	v_add_f32_e32 v141, v141, v149
	v_add_f32_e32 v142, v142, v150
	v_add_f32_e32 v143, v143, v151
	v_mov_b32_e32 v144, v136
	v_mov_b32_e32 v145, v137
	v_mov_b32_e32 v146, v138
	v_mov_b32_e32 v147, v139
	v_mov_b32_e32 v148, v140
	v_mov_b32_e32 v149, v141
	v_mov_b32_e32 v150, v142
	v_mov_b32_e32 v151, v143
	s_nop 1
	v_permlane32_swap_b32 v136, v144
	v_permlane32_swap_b32 v137, v145
	v_permlane32_swap_b32 v138, v146
	v_permlane32_swap_b32 v139, v147
	v_permlane32_swap_b32 v140, v148
	v_permlane32_swap_b32 v141, v149
	v_permlane32_swap_b32 v142, v150
	v_permlane32_swap_b32 v143, v151
	s_nop 1
	v_add_f32_e32 v136, v136, v144
	v_add_f32_e32 v137, v137, v145
	v_add_f32_e32 v138, v138, v146
	v_add_f32_e32 v139, v139, v147
	v_add_f32_e32 v140, v140, v148
	v_add_f32_e32 v141, v141, v149
	v_add_f32_e32 v142, v142, v150
	v_add_f32_e32 v143, v143, v151
	v_cvt_pk_bf16_f32 v152, v126, v127
	v_cvt_pk_bf16_f32 v153, v128, v129
	v_cvt_pk_bf16_f32 v154, v122, v123
	v_cvt_pk_bf16_f32 v155, v124, v125
	global_store_dwordx4 v130, v[152:155], s[6:7] sc1
	s_add_u32 s6, s6, s33
	s_addc_u32 s7, s7, 0
	v_cvt_pk_bf16_f32 v152, v108, v109
	v_cvt_pk_bf16_f32 v153, v110, v111
	v_cvt_pk_bf16_f32 v154, v104, v105
	v_cvt_pk_bf16_f32 v155, v106, v107
	global_store_dwordx4 v130, v[152:155], s[6:7] sc1
	s_add_u32 s6, s6, s33
	s_addc_u32 s7, s7, 0
	v_cvt_pk_bf16_f32 v152, v92, v93
	v_cvt_pk_bf16_f32 v153, v94, v95
	v_cvt_pk_bf16_f32 v154, v88, v89
	v_cvt_pk_bf16_f32 v155, v90, v91
	global_store_dwordx4 v130, v[152:155], s[6:7] sc1
	s_add_u32 s6, s6, s33
	s_addc_u32 s7, s7, 0
	v_cvt_pk_bf16_f32 v152, v76, v77
	v_cvt_pk_bf16_f32 v153, v78, v79
	v_cvt_pk_bf16_f32 v154, v72, v73
	v_cvt_pk_bf16_f32 v155, v74, v75
	global_store_dwordx4 v130, v[152:155], s[6:7] sc1
	s_add_u32 s6, s6, s34
	s_addc_u32 s7, s7, 0
	v_cvt_pk_bf16_f32 v152, v60, v61
	v_cvt_pk_bf16_f32 v153, v62, v63
	v_cvt_pk_bf16_f32 v154, v56, v57
	v_cvt_pk_bf16_f32 v155, v58, v59
	global_store_dwordx4 v130, v[152:155], s[6:7] sc1
	s_add_u32 s6, s6, s33
	s_addc_u32 s7, s7, 0
	v_cvt_pk_bf16_f32 v152, v44, v45
	v_cvt_pk_bf16_f32 v153, v46, v47
	v_cvt_pk_bf16_f32 v154, v40, v41
	v_cvt_pk_bf16_f32 v155, v42, v43
	global_store_dwordx4 v130, v[152:155], s[6:7] sc1
	s_add_u32 s6, s6, s33
	s_addc_u32 s7, s7, 0
	v_cvt_pk_bf16_f32 v152, v28, v29
	v_cvt_pk_bf16_f32 v153, v30, v31
	v_cvt_pk_bf16_f32 v154, v24, v25
	v_cvt_pk_bf16_f32 v155, v26, v27
	global_store_dwordx4 v130, v[152:155], s[6:7] sc1
	s_add_u32 s6, s6, s33
	s_addc_u32 s7, s7, 0
	v_cvt_pk_bf16_f32 v152, v12, v13
	v_cvt_pk_bf16_f32 v153, v14, v15
	v_cvt_pk_bf16_f32 v154, v4, v5
	v_cvt_pk_bf16_f32 v155, v6, v7
	global_store_dwordx4 v130, v[152:155], s[6:7] sc1
	v_cndmask_b32_e64 v160, v136, v137, s[50:51]
	v_cndmask_b32_e64 v160, v160, v138, s[58:59]
	v_cndmask_b32_e64 v160, v160, v139, s[96:97]
	v_cndmask_b32_e64 v161, v140, v141, s[50:51]
	v_cndmask_b32_e64 v161, v161, v142, s[58:59]
	v_cndmask_b32_e64 v161, v161, v143, s[96:97]
	global_store_dword v134, v160, s[24:25] sc1
	s_add_u32 s24, s24, s35
	s_addc_u32 s25, s25, 0
	global_store_dword v134, v161, s[24:25] sc1
	s_branch .LBB0_872
.Lm0_P2b:
	v_cmp_eq_u32_e64 s[50:51], 1, v191
	v_cmp_eq_u32_e64 s[58:59], 2, v191
	v_cmp_eq_u32_e64 s[96:97], 3, v191
	v_mul_f32_e32 v136, v127, v127
	v_fmac_f32_e32 v136, v126, v126
	v_fmac_f32_e32 v136, v128, v128
	v_mul_f32_e32 v160, v129, v129
	v_mul_f32_e32 v161, v123, v123
	v_add_f32_e32 v136, v160, v136
	v_fmac_f32_e32 v136, v122, v122
	v_mul_f32_e32 v160, v125, v125
	v_add_f32_e32 v136, v161, v136
	v_fmac_f32_e32 v136, v124, v124
	v_add_f32_e32 v136, v160, v136
	v_mul_f32_e32 v137, v109, v109
	v_fmac_f32_e32 v137, v108, v108
	v_fmac_f32_e32 v137, v110, v110
	v_mul_f32_e32 v160, v111, v111
	v_mul_f32_e32 v161, v105, v105
	v_add_f32_e32 v137, v160, v137
	v_fmac_f32_e32 v137, v104, v104
	v_mul_f32_e32 v160, v107, v107
	v_add_f32_e32 v137, v161, v137
	v_fmac_f32_e32 v137, v106, v106
	v_add_f32_e32 v137, v160, v137
	v_mul_f32_e32 v138, v93, v93
	v_fmac_f32_e32 v138, v92, v92
	v_fmac_f32_e32 v138, v94, v94
	v_mul_f32_e32 v160, v95, v95
	v_mul_f32_e32 v161, v89, v89
	v_add_f32_e32 v138, v160, v138
	v_fmac_f32_e32 v138, v88, v88
	v_mul_f32_e32 v160, v91, v91
	v_add_f32_e32 v138, v161, v138
	v_fmac_f32_e32 v138, v90, v90
	v_add_f32_e32 v138, v160, v138
	v_mul_f32_e32 v139, v77, v77
	v_fmac_f32_e32 v139, v76, v76
	v_fmac_f32_e32 v139, v78, v78
	v_mul_f32_e32 v160, v79, v79
	v_mul_f32_e32 v161, v73, v73
	v_add_f32_e32 v139, v160, v139
	v_fmac_f32_e32 v139, v72, v72
	v_mul_f32_e32 v160, v75, v75
	v_add_f32_e32 v139, v161, v139
	v_fmac_f32_e32 v139, v74, v74
	v_add_f32_e32 v139, v160, v139
	v_mul_f32_e32 v140, v61, v61
	v_fmac_f32_e32 v140, v60, v60
	v_fmac_f32_e32 v140, v62, v62
	v_mul_f32_e32 v160, v63, v63
	v_mul_f32_e32 v161, v57, v57
	v_add_f32_e32 v140, v160, v140
	v_fmac_f32_e32 v140, v56, v56
	v_mul_f32_e32 v160, v59, v59
	v_add_f32_e32 v140, v161, v140
	v_fmac_f32_e32 v140, v58, v58
	v_add_f32_e32 v140, v160, v140
	v_mul_f32_e32 v141, v45, v45
	v_fmac_f32_e32 v141, v44, v44
	v_fmac_f32_e32 v141, v46, v46
	v_mul_f32_e32 v160, v47, v47
	v_mul_f32_e32 v161, v41, v41
	v_add_f32_e32 v141, v160, v141
	v_fmac_f32_e32 v141, v40, v40
	v_mul_f32_e32 v160, v43, v43
	v_add_f32_e32 v141, v161, v141
	v_fmac_f32_e32 v141, v42, v42
	v_add_f32_e32 v141, v160, v141
	v_mul_f32_e32 v142, v29, v29
	v_fmac_f32_e32 v142, v28, v28
	v_fmac_f32_e32 v142, v30, v30
	v_mul_f32_e32 v160, v31, v31
	v_mul_f32_e32 v161, v25, v25
	v_add_f32_e32 v142, v160, v142
	v_fmac_f32_e32 v142, v24, v24
	v_mul_f32_e32 v160, v27, v27
	v_add_f32_e32 v142, v161, v142
	v_fmac_f32_e32 v142, v26, v26
	v_add_f32_e32 v142, v160, v142
	v_mul_f32_e32 v143, v13, v13
	v_fmac_f32_e32 v143, v12, v12
	v_fmac_f32_e32 v143, v14, v14
	v_mul_f32_e32 v160, v15, v15
	v_mul_f32_e32 v161, v5, v5
	v_add_f32_e32 v143, v160, v143
	v_fmac_f32_e32 v143, v4, v4
	v_mul_f32_e32 v160, v7, v7
	v_add_f32_e32 v143, v161, v143
	v_fmac_f32_e32 v143, v6, v6
	v_add_f32_e32 v143, v160, v143
	ds_swizzle_b32 v144, v136 offset:swizzle(SWAP,16)
	ds_swizzle_b32 v145, v137 offset:swizzle(SWAP,16)
	ds_swizzle_b32 v146, v138 offset:swizzle(SWAP,16)
	ds_swizzle_b32 v147, v139 offset:swizzle(SWAP,16)
	ds_swizzle_b32 v148, v140 offset:swizzle(SWAP,16)
	ds_swizzle_b32 v149, v141 offset:swizzle(SWAP,16)
	ds_swizzle_b32 v150, v142 offset:swizzle(SWAP,16)
	ds_swizzle_b32 v151, v143 offset:swizzle(SWAP,16)
	s_waitcnt lgkmcnt(0)
	v_add_f32_e32 v136, v136, v144
	v_add_f32_e32 v137, v137, v145
	v_add_f32_e32 v138, v138, v146
	v_add_f32_e32 v139, v139, v147
	v_add_f32_e32 v140, v140, v148
	v_add_f32_e32 v141, v141, v149
	v_add_f32_e32 v142, v142, v150
	v_add_f32_e32 v143, v143, v151
	v_mov_b32_e32 v144, v136
	v_mov_b32_e32 v145, v137
	v_mov_b32_e32 v146, v138
	v_mov_b32_e32 v147, v139
	v_mov_b32_e32 v148, v140
	v_mov_b32_e32 v149, v141
	v_mov_b32_e32 v150, v142
	v_mov_b32_e32 v151, v143
	s_nop 1
	v_permlane32_swap_b32 v136, v144
	v_permlane32_swap_b32 v137, v145
	v_permlane32_swap_b32 v138, v146
	v_permlane32_swap_b32 v139, v147
	v_permlane32_swap_b32 v140, v148
	v_permlane32_swap_b32 v141, v149
	v_permlane32_swap_b32 v142, v150
	v_permlane32_swap_b32 v143, v151
	s_nop 1
	v_add_f32_e32 v136, v136, v144
	v_add_f32_e32 v137, v137, v145
	v_add_f32_e32 v138, v138, v146
	v_add_f32_e32 v139, v139, v147
	v_add_f32_e32 v140, v140, v148
	v_add_f32_e32 v141, v141, v149
	v_add_f32_e32 v142, v142, v150
	v_add_f32_e32 v143, v143, v151
	v_cvt_pk_bf16_f32 v152, v126, v127
	v_cvt_pk_bf16_f32 v153, v128, v129
	v_cvt_pk_bf16_f32 v154, v122, v123
	v_cvt_pk_bf16_f32 v155, v124, v125
	global_store_dwordx4 v130, v[152:155], s[6:7] sc1
	s_add_u32 s6, s6, s33
	s_addc_u32 s7, s7, 0
	v_cvt_pk_bf16_f32 v156, v118, v119
	v_cvt_pk_bf16_f32 v157, v120, v121
	v_cvt_pk_bf16_f32 v158, v114, v115
	v_cvt_pk_bf16_f32 v159, v116, v117
	global_store_dwordx4 v131, v[156:159], s[48:49]
	s_add_u32 s48, s48, 0x400
	s_addc_u32 s49, s49, 0
	v_cvt_pk_bf16_f32 v152, v108, v109
	v_cvt_pk_bf16_f32 v153, v110, v111
	v_cvt_pk_bf16_f32 v154, v104, v105
	v_cvt_pk_bf16_f32 v155, v106, v107
	global_store_dwordx4 v130, v[152:155], s[6:7] sc1
	s_add_u32 s6, s6, s33
	s_addc_u32 s7, s7, 0
	v_cvt_pk_bf16_f32 v156, v100, v101
	v_cvt_pk_bf16_f32 v157, v102, v103
	v_cvt_pk_bf16_f32 v158, v96, v97
	v_cvt_pk_bf16_f32 v159, v98, v99
	global_store_dwordx4 v131, v[156:159], s[48:49]
	s_add_u32 s48, s48, 0x400
	s_addc_u32 s49, s49, 0
	v_cvt_pk_bf16_f32 v152, v92, v93
	v_cvt_pk_bf16_f32 v153, v94, v95
	v_cvt_pk_bf16_f32 v154, v88, v89
	v_cvt_pk_bf16_f32 v155, v90, v91
	global_store_dwordx4 v130, v[152:155], s[6:7] sc1
	s_add_u32 s6, s6, s33
	s_addc_u32 s7, s7, 0
	v_cvt_pk_bf16_f32 v156, v84, v85
	v_cvt_pk_bf16_f32 v157, v86, v87
	v_cvt_pk_bf16_f32 v158, v80, v81
	v_cvt_pk_bf16_f32 v159, v82, v83
	global_store_dwordx4 v131, v[156:159], s[48:49]
	s_add_u32 s48, s48, 0x400
	s_addc_u32 s49, s49, 0
	v_cvt_pk_bf16_f32 v152, v76, v77
	v_cvt_pk_bf16_f32 v153, v78, v79
	v_cvt_pk_bf16_f32 v154, v72, v73
	v_cvt_pk_bf16_f32 v155, v74, v75
	global_store_dwordx4 v130, v[152:155], s[6:7] sc1
	s_add_u32 s6, s6, s34
	s_addc_u32 s7, s7, 0
	v_cvt_pk_bf16_f32 v156, v68, v69
	v_cvt_pk_bf16_f32 v157, v70, v71
	v_cvt_pk_bf16_f32 v158, v64, v65
	v_cvt_pk_bf16_f32 v159, v66, v67
	global_store_dwordx4 v131, v[156:159], s[48:49]
	s_add_u32 s48, s48, 0x1400
	s_addc_u32 s49, s49, 0
	v_cvt_pk_bf16_f32 v152, v60, v61
	v_cvt_pk_bf16_f32 v153, v62, v63
	v_cvt_pk_bf16_f32 v154, v56, v57
	v_cvt_pk_bf16_f32 v155, v58, v59
	global_store_dwordx4 v130, v[152:155], s[6:7] sc1
	s_add_u32 s6, s6, s33
	s_addc_u32 s7, s7, 0
	v_cvt_pk_bf16_f32 v156, v52, v53
	v_cvt_pk_bf16_f32 v157, v54, v55
	v_cvt_pk_bf16_f32 v158, v48, v49
	v_cvt_pk_bf16_f32 v159, v50, v51
	global_store_dwordx4 v131, v[156:159], s[48:49]
	s_add_u32 s48, s48, 0x400
	s_addc_u32 s49, s49, 0
	v_cvt_pk_bf16_f32 v152, v44, v45
	v_cvt_pk_bf16_f32 v153, v46, v47
	v_cvt_pk_bf16_f32 v154, v40, v41
	v_cvt_pk_bf16_f32 v155, v42, v43
	global_store_dwordx4 v130, v[152:155], s[6:7] sc1
	s_add_u32 s6, s6, s33
	s_addc_u32 s7, s7, 0
	v_cvt_pk_bf16_f32 v156, v36, v37
	v_cvt_pk_bf16_f32 v157, v38, v39
	v_cvt_pk_bf16_f32 v158, v32, v33
	v_cvt_pk_bf16_f32 v159, v34, v35
	global_store_dwordx4 v131, v[156:159], s[48:49]
	s_add_u32 s48, s48, 0x400
	s_addc_u32 s49, s49, 0
	v_cvt_pk_bf16_f32 v152, v28, v29
	v_cvt_pk_bf16_f32 v153, v30, v31
	v_cvt_pk_bf16_f32 v154, v24, v25
	v_cvt_pk_bf16_f32 v155, v26, v27
	global_store_dwordx4 v130, v[152:155], s[6:7] sc1
	s_add_u32 s6, s6, s33
	s_addc_u32 s7, s7, 0
	v_cvt_pk_bf16_f32 v156, v20, v21
	v_cvt_pk_bf16_f32 v157, v22, v23
	v_cvt_pk_bf16_f32 v158, v16, v17
	v_cvt_pk_bf16_f32 v159, v18, v19
	global_store_dwordx4 v131, v[156:159], s[48:49]
	s_add_u32 s48, s48, 0x400
	s_addc_u32 s49, s49, 0
	v_cvt_pk_bf16_f32 v152, v12, v13
	v_cvt_pk_bf16_f32 v153, v14, v15
	v_cvt_pk_bf16_f32 v154, v4, v5
	v_cvt_pk_bf16_f32 v155, v6, v7
	global_store_dwordx4 v130, v[152:155], s[6:7] sc1
	v_cvt_pk_bf16_f32 v156, v8, v9
	v_cvt_pk_bf16_f32 v157, v10, v11
	v_cvt_pk_bf16_f32 v158, v0, v1
	v_cvt_pk_bf16_f32 v159, v2, v3
	global_store_dwordx4 v131, v[156:159], s[48:49]
	v_cndmask_b32_e64 v160, v136, v137, s[50:51]
	v_cndmask_b32_e64 v160, v160, v138, s[58:59]
	v_cndmask_b32_e64 v160, v160, v139, s[96:97]
	v_cndmask_b32_e64 v161, v140, v141, s[50:51]
	v_cndmask_b32_e64 v161, v161, v142, s[58:59]
	v_cndmask_b32_e64 v161, v161, v143, s[96:97]
	global_store_dword v134, v160, s[24:25] sc1
	s_add_u32 s24, s24, s35
	s_addc_u32 s25, s25, 0
	global_store_dword v134, v161, s[24:25] sc1
	s_branch .LBB0_872
.Lm0_P2c:
	global_load_dwordx4 v[164:167], v132, s[8:9]
	global_load_dwordx4 v[168:171], v133, s[8:9]
	v_cmp_eq_u32_e64 s[50:51], 1, v191
	v_cmp_eq_u32_e64 s[58:59], 2, v191
	v_cmp_eq_u32_e64 s[96:97], 3, v191
	v_mul_f32_e32 v136, v127, v127
	v_fmac_f32_e32 v136, v126, v126
	v_fmac_f32_e32 v136, v128, v128
	v_mul_f32_e32 v160, v129, v129
	v_mul_f32_e32 v161, v123, v123
	v_add_f32_e32 v136, v160, v136
	v_fmac_f32_e32 v136, v122, v122
	v_mul_f32_e32 v160, v125, v125
	v_add_f32_e32 v136, v161, v136
	v_fmac_f32_e32 v136, v124, v124
	v_add_f32_e32 v136, v160, v136
	v_mul_f32_e32 v137, v109, v109
	v_fmac_f32_e32 v137, v108, v108
	v_fmac_f32_e32 v137, v110, v110
	v_mul_f32_e32 v160, v111, v111
	v_mul_f32_e32 v161, v105, v105
	v_add_f32_e32 v137, v160, v137
	v_fmac_f32_e32 v137, v104, v104
	v_mul_f32_e32 v160, v107, v107
	v_add_f32_e32 v137, v161, v137
	v_fmac_f32_e32 v137, v106, v106
	v_add_f32_e32 v137, v160, v137
	v_mul_f32_e32 v138, v93, v93
	v_fmac_f32_e32 v138, v92, v92
	v_fmac_f32_e32 v138, v94, v94
	v_mul_f32_e32 v160, v95, v95
	v_mul_f32_e32 v161, v89, v89
	v_add_f32_e32 v138, v160, v138
	v_fmac_f32_e32 v138, v88, v88
	v_mul_f32_e32 v160, v91, v91
	v_add_f32_e32 v138, v161, v138
	v_fmac_f32_e32 v138, v90, v90
	v_add_f32_e32 v138, v160, v138
	v_mul_f32_e32 v139, v77, v77
	v_fmac_f32_e32 v139, v76, v76
	v_fmac_f32_e32 v139, v78, v78
	v_mul_f32_e32 v160, v79, v79
	v_mul_f32_e32 v161, v73, v73
	v_add_f32_e32 v139, v160, v139
	v_fmac_f32_e32 v139, v72, v72
	v_mul_f32_e32 v160, v75, v75
	v_add_f32_e32 v139, v161, v139
	v_fmac_f32_e32 v139, v74, v74
	v_add_f32_e32 v139, v160, v139
	v_mul_f32_e32 v140, v61, v61
	v_fmac_f32_e32 v140, v60, v60
	v_fmac_f32_e32 v140, v62, v62
	v_mul_f32_e32 v160, v63, v63
	v_mul_f32_e32 v161, v57, v57
	v_add_f32_e32 v140, v160, v140
	v_fmac_f32_e32 v140, v56, v56
	v_mul_f32_e32 v160, v59, v59
	v_add_f32_e32 v140, v161, v140
	v_fmac_f32_e32 v140, v58, v58
	v_add_f32_e32 v140, v160, v140
	v_mul_f32_e32 v141, v45, v45
	v_fmac_f32_e32 v141, v44, v44
	v_fmac_f32_e32 v141, v46, v46
	v_mul_f32_e32 v160, v47, v47
	v_mul_f32_e32 v161, v41, v41
	v_add_f32_e32 v141, v160, v141
	v_fmac_f32_e32 v141, v40, v40
	v_mul_f32_e32 v160, v43, v43
	v_add_f32_e32 v141, v161, v141
	v_fmac_f32_e32 v141, v42, v42
	v_add_f32_e32 v141, v160, v141
	v_mul_f32_e32 v142, v29, v29
	v_fmac_f32_e32 v142, v28, v28
	v_fmac_f32_e32 v142, v30, v30
	v_mul_f32_e32 v160, v31, v31
	v_mul_f32_e32 v161, v25, v25
	v_add_f32_e32 v142, v160, v142
	v_fmac_f32_e32 v142, v24, v24
	v_mul_f32_e32 v160, v27, v27
	v_add_f32_e32 v142, v161, v142
	v_fmac_f32_e32 v142, v26, v26
	v_add_f32_e32 v142, v160, v142
	v_mul_f32_e32 v143, v13, v13
	v_fmac_f32_e32 v143, v12, v12
	v_fmac_f32_e32 v143, v14, v14
	v_mul_f32_e32 v160, v15, v15
	v_mul_f32_e32 v161, v5, v5
	v_add_f32_e32 v143, v160, v143
	v_fmac_f32_e32 v143, v4, v4
	v_mul_f32_e32 v160, v7, v7
	v_add_f32_e32 v143, v161, v143
	v_fmac_f32_e32 v143, v6, v6
	v_add_f32_e32 v143, v160, v143
	ds_swizzle_b32 v144, v136 offset:swizzle(SWAP,16)
	ds_swizzle_b32 v145, v137 offset:swizzle(SWAP,16)
	ds_swizzle_b32 v146, v138 offset:swizzle(SWAP,16)
	ds_swizzle_b32 v147, v139 offset:swizzle(SWAP,16)
	ds_swizzle_b32 v148, v140 offset:swizzle(SWAP,16)
	ds_swizzle_b32 v149, v141 offset:swizzle(SWAP,16)
	ds_swizzle_b32 v150, v142 offset:swizzle(SWAP,16)
	ds_swizzle_b32 v151, v143 offset:swizzle(SWAP,16)
	s_waitcnt lgkmcnt(0)
	v_add_f32_e32 v136, v136, v144
	v_add_f32_e32 v137, v137, v145
	v_add_f32_e32 v138, v138, v146
	v_add_f32_e32 v139, v139, v147
	v_add_f32_e32 v140, v140, v148
	v_add_f32_e32 v141, v141, v149
	v_add_f32_e32 v142, v142, v150
	v_add_f32_e32 v143, v143, v151
	v_mov_b32_e32 v144, v136
	v_mov_b32_e32 v145, v137
	v_mov_b32_e32 v146, v138
	v_mov_b32_e32 v147, v139
	v_mov_b32_e32 v148, v140
	v_mov_b32_e32 v149, v141
	v_mov_b32_e32 v150, v142
	v_mov_b32_e32 v151, v143
	s_nop 1
	v_permlane32_swap_b32 v136, v144
	v_permlane32_swap_b32 v137, v145
	v_permlane32_swap_b32 v138, v146
	v_permlane32_swap_b32 v139, v147
	v_permlane32_swap_b32 v140, v148
	v_permlane32_swap_b32 v141, v149
	v_permlane32_swap_b32 v142, v150
	v_permlane32_swap_b32 v143, v151
	s_nop 1
	v_add_f32_e32 v136, v136, v144
	v_add_f32_e32 v137, v137, v145
	v_add_f32_e32 v138, v138, v146
	v_add_f32_e32 v139, v139, v147
	v_add_f32_e32 v140, v140, v148
	v_add_f32_e32 v141, v141, v149
	v_add_f32_e32 v142, v142, v150
	v_add_f32_e32 v143, v143, v151
	s_add_u32 s8, s8, 0x400
	s_addc_u32 s9, s9, 0
	global_load_dwordx4 v[172:175], v132, s[8:9]
	global_load_dwordx4 v[176:179], v133, s[8:9]
	v_cvt_pk_bf16_f32 v152, v126, v127
	v_cvt_pk_bf16_f32 v153, v128, v129
	v_cvt_pk_bf16_f32 v154, v122, v123
	v_cvt_pk_bf16_f32 v155, v124, v125
	global_store_dwordx4 v130, v[152:155], s[6:7] sc1
	s_add_u32 s6, s6, s33
	s_addc_u32 s7, s7, 0
	s_waitcnt vmcnt(3)
	v_pk_mul_f32 v[162:163], v[118:119], v[168:169] op_sel:[1,0] op_sel_hi:[0,0]
	v_pk_fma_f32 v[118:119], v[118:119], v[164:165], v[162:163] op_sel:[0,0,0] op_sel_hi:[1,0,1] neg_lo:[0,0,1]
	v_pk_mul_f32 v[162:163], v[120:121], v[168:169] op_sel:[1,1] op_sel_hi:[0,1]
	v_pk_fma_f32 v[120:121], v[120:121], v[164:165], v[162:163] op_sel:[0,1,0] op_sel_hi:[1,1,1] neg_lo:[0,0,1]
	v_pk_mul_f32 v[162:163], v[114:115], v[170:171] op_sel:[1,0] op_sel_hi:[0,0]
	v_pk_fma_f32 v[114:115], v[114:115], v[166:167], v[162:163] op_sel:[0,0,0] op_sel_hi:[1,0,1] neg_lo:[0,0,1]
	v_pk_mul_f32 v[162:163], v[116:117], v[170:171] op_sel:[1,1] op_sel_hi:[0,1]
	v_pk_fma_f32 v[116:117], v[116:117], v[166:167], v[162:163] op_sel:[0,1,0] op_sel_hi:[1,1,1] neg_lo:[0,0,1]
	v_cvt_pk_bf16_f32 v156, v118, v119
	v_cvt_pk_bf16_f32 v157, v120, v121
	v_cvt_pk_bf16_f32 v158, v114, v115
	v_cvt_pk_bf16_f32 v159, v116, v117
	global_store_dwordx4 v131, v[156:159], s[48:49]
	s_add_u32 s48, s48, 0x400
	s_addc_u32 s49, s49, 0
	s_add_u32 s8, s8, 0x400
	s_addc_u32 s9, s9, 0
	global_load_dwordx4 v[164:167], v132, s[8:9]
	global_load_dwordx4 v[168:171], v133, s[8:9]
	v_cvt_pk_bf16_f32 v152, v108, v109
	v_cvt_pk_bf16_f32 v153, v110, v111
	v_cvt_pk_bf16_f32 v154, v104, v105
	v_cvt_pk_bf16_f32 v155, v106, v107
	global_store_dwordx4 v130, v[152:155], s[6:7] sc1
	s_add_u32 s6, s6, s33
	s_addc_u32 s7, s7, 0
	s_waitcnt vmcnt(5)
	v_pk_mul_f32 v[162:163], v[100:101], v[176:177] op_sel:[1,0] op_sel_hi:[0,0]
	v_pk_fma_f32 v[100:101], v[100:101], v[172:173], v[162:163] op_sel:[0,0,0] op_sel_hi:[1,0,1] neg_lo:[0,0,1]
	v_pk_mul_f32 v[162:163], v[102:103], v[176:177] op_sel:[1,1] op_sel_hi:[0,1]
	v_pk_fma_f32 v[102:103], v[102:103], v[172:173], v[162:163] op_sel:[0,1,0] op_sel_hi:[1,1,1] neg_lo:[0,0,1]
	v_pk_mul_f32 v[162:163], v[96:97], v[178:179] op_sel:[1,0] op_sel_hi:[0,0]
	v_pk_fma_f32 v[96:97], v[96:97], v[174:175], v[162:163] op_sel:[0,0,0] op_sel_hi:[1,0,1] neg_lo:[0,0,1]
	v_pk_mul_f32 v[162:163], v[98:99], v[178:179] op_sel:[1,1] op_sel_hi:[0,1]
	v_pk_fma_f32 v[98:99], v[98:99], v[174:175], v[162:163] op_sel:[0,1,0] op_sel_hi:[1,1,1] neg_lo:[0,0,1]
	v_cvt_pk_bf16_f32 v156, v100, v101
	v_cvt_pk_bf16_f32 v157, v102, v103
	v_cvt_pk_bf16_f32 v158, v96, v97
	v_cvt_pk_bf16_f32 v159, v98, v99
	global_store_dwordx4 v131, v[156:159], s[48:49]
	s_add_u32 s48, s48, 0x400
	s_addc_u32 s49, s49, 0
	s_add_u32 s8, s8, 0x400
	s_addc_u32 s9, s9, 0
	global_load_dwordx4 v[172:175], v132, s[8:9]
	global_load_dwordx4 v[176:179], v133, s[8:9]
	v_cvt_pk_bf16_f32 v152, v92, v93
	v_cvt_pk_bf16_f32 v153, v94, v95
	v_cvt_pk_bf16_f32 v154, v88, v89
	v_cvt_pk_bf16_f32 v155, v90, v91
	global_store_dwordx4 v130, v[152:155], s[6:7] sc1
	s_add_u32 s6, s6, s33
	s_addc_u32 s7, s7, 0
	s_waitcnt vmcnt(5)
	v_pk_mul_f32 v[162:163], v[84:85], v[168:169] op_sel:[1,0] op_sel_hi:[0,0]
	v_pk_fma_f32 v[84:85], v[84:85], v[164:165], v[162:163] op_sel:[0,0,0] op_sel_hi:[1,0,1] neg_lo:[0,0,1]
	v_pk_mul_f32 v[162:163], v[86:87], v[168:169] op_sel:[1,1] op_sel_hi:[0,1]
	v_pk_fma_f32 v[86:87], v[86:87], v[164:165], v[162:163] op_sel:[0,1,0] op_sel_hi:[1,1,1] neg_lo:[0,0,1]
	v_pk_mul_f32 v[162:163], v[80:81], v[170:171] op_sel:[1,0] op_sel_hi:[0,0]
	v_pk_fma_f32 v[80:81], v[80:81], v[166:167], v[162:163] op_sel:[0,0,0] op_sel_hi:[1,0,1] neg_lo:[0,0,1]
	v_pk_mul_f32 v[162:163], v[82:83], v[170:171] op_sel:[1,1] op_sel_hi:[0,1]
	v_pk_fma_f32 v[82:83], v[82:83], v[166:167], v[162:163] op_sel:[0,1,0] op_sel_hi:[1,1,1] neg_lo:[0,0,1]
	v_cvt_pk_bf16_f32 v156, v84, v85
	v_cvt_pk_bf16_f32 v157, v86, v87
	v_cvt_pk_bf16_f32 v158, v80, v81
	v_cvt_pk_bf16_f32 v159, v82, v83
	global_store_dwordx4 v131, v[156:159], s[48:49]
	s_add_u32 s48, s48, 0x400
	s_addc_u32 s49, s49, 0
	s_add_u32 s8, s8, 0x1400
	s_addc_u32 s9, s9, 0
	global_load_dwordx4 v[164:167], v132, s[8:9]
	global_load_dwordx4 v[168:171], v133, s[8:9]
	v_cvt_pk_bf16_f32 v152, v76, v77
	v_cvt_pk_bf16_f32 v153, v78, v79
	v_cvt_pk_bf16_f32 v154, v72, v73
	v_cvt_pk_bf16_f32 v155, v74, v75
	global_store_dwordx4 v130, v[152:155], s[6:7] sc1
	s_add_u32 s6, s6, s34
	s_addc_u32 s7, s7, 0
	s_waitcnt vmcnt(5)
	v_pk_mul_f32 v[162:163], v[68:69], v[176:177] op_sel:[1,0] op_sel_hi:[0,0]
	v_pk_fma_f32 v[68:69], v[68:69], v[172:173], v[162:163] op_sel:[0,0,0] op_sel_hi:[1,0,1] neg_lo:[0,0,1]
	v_pk_mul_f32 v[162:163], v[70:71], v[176:177] op_sel:[1,1] op_sel_hi:[0,1]
	v_pk_fma_f32 v[70:71], v[70:71], v[172:173], v[162:163] op_sel:[0,1,0] op_sel_hi:[1,1,1] neg_lo:[0,0,1]
	v_pk_mul_f32 v[162:163], v[64:65], v[178:179] op_sel:[1,0] op_sel_hi:[0,0]
	v_pk_fma_f32 v[64:65], v[64:65], v[174:175], v[162:163] op_sel:[0,0,0] op_sel_hi:[1,0,1] neg_lo:[0,0,1]
	v_pk_mul_f32 v[162:163], v[66:67], v[178:179] op_sel:[1,1] op_sel_hi:[0,1]
	v_pk_fma_f32 v[66:67], v[66:67], v[174:175], v[162:163] op_sel:[0,1,0] op_sel_hi:[1,1,1] neg_lo:[0,0,1]
	v_cvt_pk_bf16_f32 v156, v68, v69
	v_cvt_pk_bf16_f32 v157, v70, v71
	v_cvt_pk_bf16_f32 v158, v64, v65
	v_cvt_pk_bf16_f32 v159, v66, v67
	global_store_dwordx4 v131, v[156:159], s[48:49]
	s_add_u32 s48, s48, 0x1400
	s_addc_u32 s49, s49, 0
	s_add_u32 s8, s8, 0x400
	s_addc_u32 s9, s9, 0
	global_load_dwordx4 v[172:175], v132, s[8:9]
	global_load_dwordx4 v[176:179], v133, s[8:9]
	v_cvt_pk_bf16_f32 v152, v60, v61
	v_cvt_pk_bf16_f32 v153, v62, v63
	v_cvt_pk_bf16_f32 v154, v56, v57
	v_cvt_pk_bf16_f32 v155, v58, v59
	global_store_dwordx4 v130, v[152:155], s[6:7] sc1
	s_add_u32 s6, s6, s33
	s_addc_u32 s7, s7, 0
	s_waitcnt vmcnt(5)
	v_pk_mul_f32 v[162:163], v[52:53], v[168:169] op_sel:[1,0] op_sel_hi:[0,0]
	v_pk_fma_f32 v[52:53], v[52:53], v[164:165], v[162:163] op_sel:[0,0,0] op_sel_hi:[1,0,1] neg_lo:[0,0,1]
	v_pk_mul_f32 v[162:163], v[54:55], v[168:169] op_sel:[1,1] op_sel_hi:[0,1]
	v_pk_fma_f32 v[54:55], v[54:55], v[164:165], v[162:163] op_sel:[0,1,0] op_sel_hi:[1,1,1] neg_lo:[0,0,1]
	v_pk_mul_f32 v[162:163], v[48:49], v[170:171] op_sel:[1,0] op_sel_hi:[0,0]
	v_pk_fma_f32 v[48:49], v[48:49], v[166:167], v[162:163] op_sel:[0,0,0] op_sel_hi:[1,0,1] neg_lo:[0,0,1]
	v_pk_mul_f32 v[162:163], v[50:51], v[170:171] op_sel:[1,1] op_sel_hi:[0,1]
	v_pk_fma_f32 v[50:51], v[50:51], v[166:167], v[162:163] op_sel:[0,1,0] op_sel_hi:[1,1,1] neg_lo:[0,0,1]
	v_cvt_pk_bf16_f32 v156, v52, v53
	v_cvt_pk_bf16_f32 v157, v54, v55
	v_cvt_pk_bf16_f32 v158, v48, v49
	v_cvt_pk_bf16_f32 v159, v50, v51
	global_store_dwordx4 v131, v[156:159], s[48:49]
	s_add_u32 s48, s48, 0x400
	s_addc_u32 s49, s49, 0
	s_add_u32 s8, s8, 0x400
	s_addc_u32 s9, s9, 0
	global_load_dwordx4 v[164:167], v132, s[8:9]
	global_load_dwordx4 v[168:171], v133, s[8:9]
	v_cvt_pk_bf16_f32 v152, v44, v45
	v_cvt_pk_bf16_f32 v153, v46, v47
	v_cvt_pk_bf16_f32 v154, v40, v41
	v_cvt_pk_bf16_f32 v155, v42, v43
	global_store_dwordx4 v130, v[152:155], s[6:7] sc1
	s_add_u32 s6, s6, s33
	s_addc_u32 s7, s7, 0
	s_waitcnt vmcnt(5)
	v_pk_mul_f32 v[162:163], v[36:37], v[176:177] op_sel:[1,0] op_sel_hi:[0,0]
	v_pk_fma_f32 v[36:37], v[36:37], v[172:173], v[162:163] op_sel:[0,0,0] op_sel_hi:[1,0,1] neg_lo:[0,0,1]
	v_pk_mul_f32 v[162:163], v[38:39], v[176:177] op_sel:[1,1] op_sel_hi:[0,1]
	v_pk_fma_f32 v[38:39], v[38:39], v[172:173], v[162:163] op_sel:[0,1,0] op_sel_hi:[1,1,1] neg_lo:[0,0,1]
	v_pk_mul_f32 v[162:163], v[32:33], v[178:179] op_sel:[1,0] op_sel_hi:[0,0]
	v_pk_fma_f32 v[32:33], v[32:33], v[174:175], v[162:163] op_sel:[0,0,0] op_sel_hi:[1,0,1] neg_lo:[0,0,1]
	v_pk_mul_f32 v[162:163], v[34:35], v[178:179] op_sel:[1,1] op_sel_hi:[0,1]
	v_pk_fma_f32 v[34:35], v[34:35], v[174:175], v[162:163] op_sel:[0,1,0] op_sel_hi:[1,1,1] neg_lo:[0,0,1]
	v_cvt_pk_bf16_f32 v156, v36, v37
	v_cvt_pk_bf16_f32 v157, v38, v39
	v_cvt_pk_bf16_f32 v158, v32, v33
	v_cvt_pk_bf16_f32 v159, v34, v35
	global_store_dwordx4 v131, v[156:159], s[48:49]
	s_add_u32 s48, s48, 0x400
	s_addc_u32 s49, s49, 0
	s_add_u32 s8, s8, 0x400
	s_addc_u32 s9, s9, 0
	global_load_dwordx4 v[172:175], v132, s[8:9]
	global_load_dwordx4 v[176:179], v133, s[8:9]
	v_cvt_pk_bf16_f32 v152, v28, v29
	v_cvt_pk_bf16_f32 v153, v30, v31
	v_cvt_pk_bf16_f32 v154, v24, v25
	v_cvt_pk_bf16_f32 v155, v26, v27
	global_store_dwordx4 v130, v[152:155], s[6:7] sc1
	s_add_u32 s6, s6, s33
	s_addc_u32 s7, s7, 0
	s_waitcnt vmcnt(5)
	v_pk_mul_f32 v[162:163], v[20:21], v[168:169] op_sel:[1,0] op_sel_hi:[0,0]
	v_pk_fma_f32 v[20:21], v[20:21], v[164:165], v[162:163] op_sel:[0,0,0] op_sel_hi:[1,0,1] neg_lo:[0,0,1]
	v_pk_mul_f32 v[162:163], v[22:23], v[168:169] op_sel:[1,1] op_sel_hi:[0,1]
	v_pk_fma_f32 v[22:23], v[22:23], v[164:165], v[162:163] op_sel:[0,1,0] op_sel_hi:[1,1,1] neg_lo:[0,0,1]
	v_pk_mul_f32 v[162:163], v[16:17], v[170:171] op_sel:[1,0] op_sel_hi:[0,0]
	v_pk_fma_f32 v[16:17], v[16:17], v[166:167], v[162:163] op_sel:[0,0,0] op_sel_hi:[1,0,1] neg_lo:[0,0,1]
	v_pk_mul_f32 v[162:163], v[18:19], v[170:171] op_sel:[1,1] op_sel_hi:[0,1]
	v_pk_fma_f32 v[18:19], v[18:19], v[166:167], v[162:163] op_sel:[0,1,0] op_sel_hi:[1,1,1] neg_lo:[0,0,1]
	v_cvt_pk_bf16_f32 v156, v20, v21
	v_cvt_pk_bf16_f32 v157, v22, v23
	v_cvt_pk_bf16_f32 v158, v16, v17
	v_cvt_pk_bf16_f32 v159, v18, v19
	global_store_dwordx4 v131, v[156:159], s[48:49]
	s_add_u32 s48, s48, 0x400
	s_addc_u32 s49, s49, 0
	v_cvt_pk_bf16_f32 v152, v12, v13
	v_cvt_pk_bf16_f32 v153, v14, v15
	v_cvt_pk_bf16_f32 v154, v4, v5
	v_cvt_pk_bf16_f32 v155, v6, v7
	global_store_dwordx4 v130, v[152:155], s[6:7] sc1
	s_waitcnt vmcnt(3)
	v_pk_mul_f32 v[162:163], v[8:9], v[176:177] op_sel:[1,0] op_sel_hi:[0,0]
	v_pk_fma_f32 v[8:9], v[8:9], v[172:173], v[162:163] op_sel:[0,0,0] op_sel_hi:[1,0,1] neg_lo:[0,0,1]
	v_pk_mul_f32 v[162:163], v[10:11], v[176:177] op_sel:[1,1] op_sel_hi:[0,1]
	v_pk_fma_f32 v[10:11], v[10:11], v[172:173], v[162:163] op_sel:[0,1,0] op_sel_hi:[1,1,1] neg_lo:[0,0,1]
	v_pk_mul_f32 v[162:163], v[0:1], v[178:179] op_sel:[1,0] op_sel_hi:[0,0]
	v_pk_fma_f32 v[0:1], v[0:1], v[174:175], v[162:163] op_sel:[0,0,0] op_sel_hi:[1,0,1] neg_lo:[0,0,1]
	v_pk_mul_f32 v[162:163], v[2:3], v[178:179] op_sel:[1,1] op_sel_hi:[0,1]
	v_pk_fma_f32 v[2:3], v[2:3], v[174:175], v[162:163] op_sel:[0,1,0] op_sel_hi:[1,1,1] neg_lo:[0,0,1]
	v_cvt_pk_bf16_f32 v156, v8, v9
	v_cvt_pk_bf16_f32 v157, v10, v11
	v_cvt_pk_bf16_f32 v158, v0, v1
	v_cvt_pk_bf16_f32 v159, v2, v3
	global_store_dwordx4 v131, v[156:159], s[48:49]
	v_cndmask_b32_e64 v160, v136, v137, s[50:51]
	v_cndmask_b32_e64 v160, v160, v138, s[58:59]
	v_cndmask_b32_e64 v160, v160, v139, s[96:97]
	v_cndmask_b32_e64 v161, v140, v141, s[50:51]
	v_cndmask_b32_e64 v161, v161, v142, s[58:59]
	v_cndmask_b32_e64 v161, v161, v143, s[96:97]
	global_store_dword v134, v160, s[24:25] sc1
	s_add_u32 s24, s24, s35
	s_addc_u32 s25, s25, 0
	global_store_dword v134, v161, s[24:25] sc1
	s_branch .LBB0_872

.LBB0_864:
	v_mov_b32_e32 v132, v155
	v_mov_b32_e32 v133, v156
	v_mov_b32_e32 v155, v157
	v_pk_add_f32 v[132:133], v[132:133], v[154:155]
	s_mov_b32 s8, 0x800000
	v_add_f32_e32 v131, v132, v133
	v_fmamk_f32 v131, v131, 0x3b800000, v242
	v_mul_f32_e32 v132, 0x4b800000, v131
	v_cmp_gt_f32_e32 vcc, s8, v131
	s_nop 1
	v_cndmask_b32_e32 v131, v131, v132, vcc
	v_rsq_f32_e32 v131, v131
	s_nop 0
	v_mul_f32_e32 v132, 0x45800000, v131
	v_cndmask_b32_e32 v132, v131, v132, vcc
	s_and_b64 vcc, exec, s[4:5]
	s_cbranch_vccz .LBB0_684
	s_branch .LBB0_685
.LBB0_872:
	s_mov_b64 s[4:5], 0
